# P5 key/value epilogue: all per-row norm loads issued once at the top, per-row-group load-then-drain steps removed
# baseline (speedup 1.0000x reference)
.LBB0_732:
	s_lshl_b32 s35, s42, 8
	s_add_i32 s35, s35, s54
	v_or_b32_e32 v144, s35, v1
	v_ashrrev_i32_e32 v145, 31, v144
	v_lshlrev_b64 v[146:147], 5, v[144:145]
	v_lshl_add_u64 v[146:147], s[10:11], 0, v[146:147]
	global_load_dwordx4 v[158:161], v[146:147], off offset:16
	global_load_dwordx4 v[182:185], v[146:147], off offset:528
	global_load_dwordx4 v[186:189], v[146:147], off offset:1040
	global_load_dwordx4 v[190:193], v[146:147], off offset:1552
	v_mov_b32_e32 v246, 0x1000
	v_mov_b32_e32 v247, 0
	v_lshl_add_u64 v[246:247], v[146:147], 0, v[246:247]
	global_load_dwordx4 v[194:197], v[246:247], off offset:16
	global_load_dwordx4 v[198:201], v[246:247], off offset:528
	global_load_dwordx4 v[202:205], v[246:247], off offset:1040
	global_load_dwordx4 v[242:245], v[246:247], off offset:1552
	s_lshl_b32 s42, s6, 1
	s_ashr_i32 s44, s35, 13
	s_ashr_i32 s43, s42, 31
	s_ashr_i32 s45, s44, 31
	v_mad_i64_i32 v[146:147], s[46:47], v144, s60, 0
	v_cndmask_b32_e64 v145, 0, 1, s[28:29]
	s_lshl_b64 s[42:43], s[42:43], 13
	s_lshl_b64 s[46:47], s[44:45], 16
	v_cmp_ne_u32_e64 s[6:7], 1, v145
	v_bitop3_b32 v145, s35, v156, v1 bitop3:0xc8
	s_add_u32 s45, s46, s42
	v_mov_b64_e32 v[148:149], s[14:15]
	v_or_b32_e32 v150, s45, v145
	s_addc_u32 s44, s47, s43
	v_mad_u64_u32 v[150:151], s[46:47], v150, s60, v[148:149]
	v_mad_i32_i24 v151, s44, v157, v151
	s_and_b64 vcc, exec, s[6:7]
	s_cbranch_vccnz .Lkv_nopref
	v_lshl_add_u64 v[238:239], v[138:139], 0, v[146:147]
	global_load_dwordx4 v[206:209], v[238:239], off offset:256
	v_add_co_u32_e32 v240, vcc, 0x1400, v238
	s_nop 1
	v_addc_co_u32_e32 v241, vcc, 0, v239, vcc
	global_load_dwordx4 v[210:213], v[240:241], off offset:256
	v_add_co_u32_e32 v240, vcc, 0x2800, v238
	s_nop 1
	v_addc_co_u32_e32 v241, vcc, 0, v239, vcc
	global_load_dwordx4 v[214:217], v[240:241], off offset:256
	v_add_co_u32_e32 v240, vcc, 0x3c00, v238
	s_nop 1
	v_addc_co_u32_e32 v241, vcc, 0, v239, vcc
	global_load_dwordx4 v[218:221], v[240:241], off offset:256
	v_add_co_u32_e32 v240, vcc, 0xa000, v238
	s_nop 1
	v_addc_co_u32_e32 v241, vcc, 0, v239, vcc
	global_load_dwordx4 v[222:225], v[240:241], off offset:256
	v_add_co_u32_e32 v240, vcc, 0xb400, v238
	s_nop 1
	v_addc_co_u32_e32 v241, vcc, 0, v239, vcc
	global_load_dwordx4 v[226:229], v[240:241], off offset:256
	v_add_co_u32_e32 v240, vcc, 0xc800, v238
	s_nop 1
	v_addc_co_u32_e32 v241, vcc, 0, v239, vcc
	global_load_dwordx4 v[230:233], v[240:241], off offset:256
	v_add_co_u32_e32 v240, vcc, 0xdc00, v238
	s_nop 1
	v_addc_co_u32_e32 v241, vcc, 0, v239, vcc
	global_load_dwordx4 v[234:237], v[240:241], off offset:256

.LBB0_736:
	s_nop 1
	v_or_b32_e32 v114, 16, v144
	v_ashrrev_i32_e32 v115, 31, v114
	v_lshlrev_b64 v[116:117], 5, v[114:115]
	v_lshl_add_u64 v[116:117], s[10:11], 0, v[116:117]
	v_mov_b32_e32 v122, v182
	v_mov_b32_e32 v123, v183
	v_mov_b32_e32 v124, v184
	v_mov_b32_e32 v125, v185
	v_bitop3_b32 v120, v144, s61, 16 bitop3:0xc8
	v_mov_b64_e32 v[116:117], s[14:15]
	v_or_b32_e32 v118, s45, v120
	v_mad_u64_u32 v[118:119], s[46:47], v118, s60, v[116:117]
	v_mad_i32_i24 v119, s44, v157, v119
	v_mad_i64_i32 v[114:115], s[46:47], v114, s60, 0
	s_and_b64 vcc, exec, s[6:7]
	v_mov_b32_e32 v116, v123
	v_mov_b32_e32 v117, v124
	v_mov_b32_e32 v123, v125
	v_pk_add_f32 v[116:117], v[116:117], v[122:123]
	v_lshl_add_u64 v[122:123], v[118:119], 0, s[8:9]
	v_add_f32_e32 v116, v116, v117
	v_fmamk_f32 v116, v116, 0x3c000000, v155
	v_rsq_f32_e32 v116, v116
	v_lshl_add_u64 v[122:123], v[122:123], 0, v[134:135]
	v_pk_mul_f32 v[110:111], v[110:111], v[116:117] op_sel_hi:[1,0]
	v_pk_mul_f32 v[106:107], v[106:107], v[116:117] op_sel_hi:[1,0]
	v_pk_mul_f32 v[112:113], v[112:113], v[116:117] op_sel_hi:[1,0]
	v_pk_mul_f32 v[108:109], v[108:109], v[116:117] op_sel_hi:[1,0]
	v_cvt_pk_bf16_f32 v110, v110, v111
	v_cvt_pk_bf16_f32 v111, v112, v113
	global_store_dwordx2 v[122:123], v[110:111], off
	v_cvt_pk_bf16_f32 v106, v106, v107
	v_cvt_pk_bf16_f32 v107, v108, v109
	global_store_dwordx2 v[122:123], v[106:107], off offset:32
	s_cbranch_vccnz .LBB0_738
	v_lshlrev_b32_e32 v110, 1, v136
	v_mov_b32_e32 v111, v135
	v_lshl_add_u64 v[110:111], v[118:119], 0, v[110:111]
	global_store_dwordx4 v[110:111], v[210:213], off offset:256

.LBB0_740:
	s_nop 1
	v_or_b32_e32 v98, 32, v144
	v_ashrrev_i32_e32 v99, 31, v98
	v_lshlrev_b64 v[100:101], 5, v[98:99]
	v_lshl_add_u64 v[100:101], s[10:11], 0, v[100:101]
	v_mov_b32_e32 v106, v186
	v_mov_b32_e32 v107, v187
	v_mov_b32_e32 v108, v188
	v_mov_b32_e32 v109, v189
	v_bitop3_b32 v104, v144, s64, 32 bitop3:0xc8
	v_mov_b64_e32 v[100:101], s[14:15]
	v_or_b32_e32 v102, s45, v104
	v_mad_u64_u32 v[102:103], s[48:49], v102, s60, v[100:101]
	v_mad_i32_i24 v103, s44, v157, v103
	v_mad_i64_i32 v[98:99], s[48:49], v98, s60, 0
	s_and_b64 vcc, exec, s[6:7]
	v_mov_b32_e32 v100, v107
	v_mov_b32_e32 v101, v108
	v_mov_b32_e32 v107, v109
	v_pk_add_f32 v[100:101], v[100:101], v[106:107]
	v_lshl_add_u64 v[106:107], v[102:103], 0, s[8:9]
	v_add_f32_e32 v100, v100, v101
	v_fmamk_f32 v100, v100, 0x3c000000, v155
	v_rsq_f32_e32 v100, v100
	v_lshl_add_u64 v[106:107], v[106:107], 0, v[134:135]
	v_pk_mul_f32 v[94:95], v[94:95], v[100:101] op_sel_hi:[1,0]
	v_pk_mul_f32 v[90:91], v[90:91], v[100:101] op_sel_hi:[1,0]
	v_pk_mul_f32 v[96:97], v[96:97], v[100:101] op_sel_hi:[1,0]
	v_pk_mul_f32 v[92:93], v[92:93], v[100:101] op_sel_hi:[1,0]
	v_cvt_pk_bf16_f32 v94, v94, v95
	v_cvt_pk_bf16_f32 v95, v96, v97
	global_store_dwordx2 v[106:107], v[94:95], off
	v_cvt_pk_bf16_f32 v90, v90, v91
	v_cvt_pk_bf16_f32 v91, v92, v93
	global_store_dwordx2 v[106:107], v[90:91], off offset:32
	s_cbranch_vccnz .LBB0_742
	v_lshlrev_b32_e32 v94, 1, v136
	v_mov_b32_e32 v95, v135
	v_lshl_add_u64 v[94:95], v[102:103], 0, v[94:95]
	global_store_dwordx4 v[94:95], v[214:217], off offset:256

.LBB0_744:
	s_nop 1
	v_or_b32_e32 v82, 48, v144
	v_ashrrev_i32_e32 v83, 31, v82
	v_lshlrev_b64 v[84:85], 5, v[82:83]
	v_lshl_add_u64 v[84:85], s[10:11], 0, v[84:85]
	v_mov_b32_e32 v90, v190
	v_mov_b32_e32 v91, v191
	v_mov_b32_e32 v92, v192
	v_mov_b32_e32 v93, v193
	v_bitop3_b32 v88, v144, s65, 48 bitop3:0xc8
	v_mov_b64_e32 v[84:85], s[14:15]
	v_or_b32_e32 v86, s45, v88
	v_mad_u64_u32 v[86:87], s[48:49], v86, s60, v[84:85]
	v_mad_i32_i24 v87, s44, v157, v87
	v_mad_i64_i32 v[82:83], s[48:49], v82, s60, 0
	s_and_b64 vcc, exec, s[6:7]
	v_mov_b32_e32 v84, v91
	v_mov_b32_e32 v85, v92
	v_mov_b32_e32 v91, v93
	v_pk_add_f32 v[84:85], v[84:85], v[90:91]
	v_lshl_add_u64 v[90:91], v[86:87], 0, s[8:9]
	v_add_f32_e32 v84, v84, v85
	v_fmamk_f32 v84, v84, 0x3c000000, v155
	v_rsq_f32_e32 v84, v84
	v_lshl_add_u64 v[90:91], v[90:91], 0, v[134:135]
	v_pk_mul_f32 v[78:79], v[78:79], v[84:85] op_sel_hi:[1,0]
	v_pk_mul_f32 v[74:75], v[74:75], v[84:85] op_sel_hi:[1,0]
	v_pk_mul_f32 v[80:81], v[80:81], v[84:85] op_sel_hi:[1,0]
	v_pk_mul_f32 v[76:77], v[76:77], v[84:85] op_sel_hi:[1,0]
	v_cvt_pk_bf16_f32 v78, v78, v79
	v_cvt_pk_bf16_f32 v79, v80, v81
	global_store_dwordx2 v[90:91], v[78:79], off
	v_cvt_pk_bf16_f32 v74, v74, v75
	v_cvt_pk_bf16_f32 v75, v76, v77
	global_store_dwordx2 v[90:91], v[74:75], off offset:32
	s_cbranch_vccnz .LBB0_746
	v_lshlrev_b32_e32 v78, 1, v136
	v_mov_b32_e32 v79, v135
	v_lshl_add_u64 v[78:79], v[86:87], 0, v[78:79]
	global_store_dwordx4 v[78:79], v[218:221], off offset:256

.LBB0_748:
	s_addk_i32 s35, 0x80
	s_nop 0
	v_or_b32_e32 v66, s35, v1
	v_ashrrev_i32_e32 v67, 31, v66
	v_lshlrev_b64 v[68:69], 5, v[66:67]
	v_lshl_add_u64 v[68:69], s[10:11], 0, v[68:69]
	v_mov_b32_e32 v74, v194
	v_mov_b32_e32 v75, v195
	v_mov_b32_e32 v76, v196
	v_mov_b32_e32 v77, v197
	s_ashr_i32 s44, s35, 13
	s_ashr_i32 s45, s44, 31
	s_lshl_b64 s[44:45], s[44:45], 16
	v_bitop3_b32 v67, s35, v156, v1 bitop3:0xc8
	s_add_u32 s37, s44, s42
	v_mov_b64_e32 v[70:71], s[14:15]
	v_or_b32_e32 v72, s37, v67
	s_addc_u32 s35, s45, s43
	v_mad_u64_u32 v[72:73], s[42:43], v72, s60, v[70:71]
	v_mad_i32_i24 v73, s35, v157, v73
	v_mad_i64_i32 v[68:69], s[46:47], v66, s60, 0
	s_and_b64 vcc, exec, s[6:7]
	v_mov_b32_e32 v70, v75
	v_mov_b32_e32 v71, v76
	v_mov_b32_e32 v75, v77
	v_pk_add_f32 v[70:71], v[70:71], v[74:75]
	v_lshl_add_u64 v[74:75], v[72:73], 0, s[8:9]
	v_add_f32_e32 v70, v70, v71
	v_fmamk_f32 v70, v70, 0x3c000000, v155
	v_rsq_f32_e32 v70, v70
	v_lshl_add_u64 v[74:75], v[74:75], 0, v[134:135]
	v_pk_mul_f32 v[62:63], v[62:63], v[70:71] op_sel_hi:[1,0]
	v_pk_mul_f32 v[58:59], v[58:59], v[70:71] op_sel_hi:[1,0]
	v_pk_mul_f32 v[64:65], v[64:65], v[70:71] op_sel_hi:[1,0]
	v_pk_mul_f32 v[60:61], v[60:61], v[70:71] op_sel_hi:[1,0]
	v_cvt_pk_bf16_f32 v62, v62, v63
	v_cvt_pk_bf16_f32 v63, v64, v65
	global_store_dwordx2 v[74:75], v[62:63], off
	v_cvt_pk_bf16_f32 v58, v58, v59
	v_cvt_pk_bf16_f32 v59, v60, v61
	global_store_dwordx2 v[74:75], v[58:59], off offset:32
	s_cbranch_vccnz .LBB0_750
	v_lshlrev_b32_e32 v62, 1, v136
	v_mov_b32_e32 v63, v135
	v_lshl_add_u64 v[62:63], v[72:73], 0, v[62:63]
	global_store_dwordx4 v[62:63], v[222:225], off offset:256

.LBB0_752:
	s_nop 1
	v_or_b32_e32 v50, 16, v66
	v_ashrrev_i32_e32 v51, 31, v50
	v_lshlrev_b64 v[52:53], 5, v[50:51]
	v_lshl_add_u64 v[52:53], s[10:11], 0, v[52:53]
	v_mov_b32_e32 v58, v198
	v_mov_b32_e32 v59, v199
	v_mov_b32_e32 v60, v200
	v_mov_b32_e32 v61, v201
	v_bitop3_b32 v56, v66, s61, 16 bitop3:0xc8
	v_mov_b64_e32 v[52:53], s[14:15]
	v_or_b32_e32 v54, s37, v56
	v_mad_u64_u32 v[54:55], s[44:45], v54, s60, v[52:53]
	v_mad_i32_i24 v55, s35, v157, v55
	v_mad_i64_i32 v[50:51], s[44:45], v50, s60, 0
	s_and_b64 vcc, exec, s[6:7]
	v_mov_b32_e32 v52, v59
	v_mov_b32_e32 v53, v60
	v_mov_b32_e32 v59, v61
	v_pk_add_f32 v[52:53], v[52:53], v[58:59]
	v_lshl_add_u64 v[58:59], v[54:55], 0, s[8:9]
	v_add_f32_e32 v52, v52, v53
	v_fmamk_f32 v52, v52, 0x3c000000, v155
	v_rsq_f32_e32 v52, v52
	v_lshl_add_u64 v[58:59], v[58:59], 0, v[134:135]
	v_pk_mul_f32 v[46:47], v[46:47], v[52:53] op_sel_hi:[1,0]
	v_pk_mul_f32 v[42:43], v[42:43], v[52:53] op_sel_hi:[1,0]
	v_pk_mul_f32 v[48:49], v[48:49], v[52:53] op_sel_hi:[1,0]
	v_pk_mul_f32 v[44:45], v[44:45], v[52:53] op_sel_hi:[1,0]
	v_cvt_pk_bf16_f32 v46, v46, v47
	v_cvt_pk_bf16_f32 v47, v48, v49
	global_store_dwordx2 v[58:59], v[46:47], off
	v_cvt_pk_bf16_f32 v42, v42, v43
	v_cvt_pk_bf16_f32 v43, v44, v45
	global_store_dwordx2 v[58:59], v[42:43], off offset:32
	s_cbranch_vccnz .LBB0_754
	v_lshlrev_b32_e32 v46, 1, v136
	v_mov_b32_e32 v47, v135
	v_lshl_add_u64 v[46:47], v[54:55], 0, v[46:47]
	global_store_dwordx4 v[46:47], v[226:229], off offset:256

.LBB0_756:
	s_nop 1
	v_or_b32_e32 v34, 32, v66
	v_ashrrev_i32_e32 v35, 31, v34
	v_lshlrev_b64 v[36:37], 5, v[34:35]
	v_lshl_add_u64 v[36:37], s[10:11], 0, v[36:37]
	v_mov_b32_e32 v42, v202
	v_mov_b32_e32 v43, v203
	v_mov_b32_e32 v44, v204
	v_mov_b32_e32 v45, v205
	v_bitop3_b32 v40, v66, s64, 32 bitop3:0xc8
	v_mov_b64_e32 v[36:37], s[14:15]
	v_or_b32_e32 v38, s37, v40
	v_mad_u64_u32 v[38:39], s[44:45], v38, s60, v[36:37]
	v_mad_i32_i24 v39, s35, v157, v39
	v_mad_i64_i32 v[34:35], s[44:45], v34, s60, 0
	s_and_b64 vcc, exec, s[6:7]
	v_mov_b32_e32 v36, v43
	v_mov_b32_e32 v37, v44
	v_mov_b32_e32 v43, v45
	v_pk_add_f32 v[36:37], v[36:37], v[42:43]
	v_lshl_add_u64 v[42:43], v[38:39], 0, s[8:9]
	v_add_f32_e32 v36, v36, v37
	v_fmamk_f32 v36, v36, 0x3c000000, v155
	v_rsq_f32_e32 v36, v36
	v_lshl_add_u64 v[42:43], v[42:43], 0, v[134:135]
	v_pk_mul_f32 v[30:31], v[30:31], v[36:37] op_sel_hi:[1,0]
	v_pk_mul_f32 v[26:27], v[26:27], v[36:37] op_sel_hi:[1,0]
	v_pk_mul_f32 v[32:33], v[32:33], v[36:37] op_sel_hi:[1,0]
	v_pk_mul_f32 v[28:29], v[28:29], v[36:37] op_sel_hi:[1,0]
	v_cvt_pk_bf16_f32 v30, v30, v31
	v_cvt_pk_bf16_f32 v31, v32, v33
	global_store_dwordx2 v[42:43], v[30:31], off
	v_cvt_pk_bf16_f32 v26, v26, v27
	v_cvt_pk_bf16_f32 v27, v28, v29
	global_store_dwordx2 v[42:43], v[26:27], off offset:32
	s_cbranch_vccnz .LBB0_758
	v_lshlrev_b32_e32 v30, 1, v136
	v_mov_b32_e32 v31, v135
	v_lshl_add_u64 v[30:31], v[38:39], 0, v[30:31]
	global_store_dwordx4 v[30:31], v[230:233], off offset:256

.LBB0_760:
	s_nop 1
	v_or_b32_e32 v18, 48, v66
	v_ashrrev_i32_e32 v19, 31, v18
	v_lshlrev_b64 v[20:21], 5, v[18:19]
	v_lshl_add_u64 v[20:21], s[10:11], 0, v[20:21]
	v_mov_b32_e32 v26, v242
	v_mov_b32_e32 v27, v243
	v_mov_b32_e32 v28, v244
	v_mov_b32_e32 v29, v245
	v_bitop3_b32 v24, v66, s65, 48 bitop3:0xc8
	v_mov_b64_e32 v[20:21], s[14:15]
	v_or_b32_e32 v22, s37, v24
	v_mad_u64_u32 v[22:23], s[44:45], v22, s60, v[20:21]
	v_mad_i32_i24 v23, s35, v157, v23
	v_mad_i64_i32 v[18:19], s[44:45], v18, s60, 0
	s_and_b64 vcc, exec, s[6:7]
	v_mov_b32_e32 v20, v27
	v_mov_b32_e32 v21, v28
	v_mov_b32_e32 v27, v29
	v_pk_add_f32 v[20:21], v[20:21], v[26:27]
	v_lshl_add_u64 v[26:27], v[22:23], 0, s[8:9]
	v_add_f32_e32 v20, v20, v21
	v_fmamk_f32 v20, v20, 0x3c000000, v155
	v_rsq_f32_e32 v20, v20
	v_lshl_add_u64 v[26:27], v[26:27], 0, v[134:135]
	v_pk_mul_f32 v[14:15], v[14:15], v[20:21] op_sel_hi:[1,0]
	v_pk_mul_f32 v[10:11], v[10:11], v[20:21] op_sel_hi:[1,0]
	v_pk_mul_f32 v[16:17], v[16:17], v[20:21] op_sel_hi:[1,0]
	v_pk_mul_f32 v[12:13], v[12:13], v[20:21] op_sel_hi:[1,0]
	v_cvt_pk_bf16_f32 v14, v14, v15
	v_cvt_pk_bf16_f32 v15, v16, v17
	global_store_dwordx2 v[26:27], v[14:15], off
	v_cvt_pk_bf16_f32 v10, v10, v11
	v_cvt_pk_bf16_f32 v11, v12, v13
	global_store_dwordx2 v[26:27], v[10:11], off offset:32
	s_cbranch_vccnz .LBB0_762
	v_lshlrev_b32_e32 v14, 1, v136
	v_mov_b32_e32 v15, v135
	v_lshl_add_u64 v[14:15], v[22:23], 0, v[14:15]
	global_store_dwordx4 v[14:15], v[234:237], off offset:256
